# attention loop: removed VALU that does nothing (0+x first add of each row sum, never-read default maxima, Q/K address copies)
# baseline (speedup 1.0000x reference)
; #define LAS __attribute__((address_space(3)))
; __device__ __forceinline__ void dattn_unit(LAS unsigned char* lds, int b, int h, int qb, const bf16* Q, const bf16* K, const bf16* V, bf16* YB, float lam, const float* subg, float oml, int tid) {
;     ...
;         if (t + 1 < NT) { const size_t adv = (size_t)(t + 1) * 64 * 1024; kr0 = *(const v4u*)(kg + adv); kr1 = *(const v4u*)(kg + adv + 64); vr0 = *(const v4u*)(vg + adv); vr1 = *(const v4u*)(vg + adv + 8); }
;         const LAS bf16* Ks = (const LAS bf16*)(lds + (t & 1) * AT_BUF + AT_KS); const LAS bf16* Vt = (const LAS bf16*)(lds + (t & 1) * AT_BUF + AT_VT);
;         const int kvbase = t * 64;
;         if (kvbase <= qmax) {
;     ...
; #pragma unroll
;         for (int sub = 0; sub < 2; ++sub) {
;             if (kvbase + 32 * sub > qmax) continue;
;             const bool need_bm = kvbase + 32 * sub + 31 + 113 > qmin;
;             LAS bf16x8* qsp = qs; asm volatile("" : "+v"(qsp));
;             f32x16 s0, s1;
; #pragma unroll
;             for (int r = 0; r < 16; ++r) { s0[r] = -mref[0]; s1[r] = -mref[1]; }
;             {
;                 const LAS bf16* kp = Ks + (32 * sub + ql) * 72 + hi * 8;
;                 bf16x8 ka = *(const LAS bf16x8*)kp, kb = *(const LAS bf16x8*)(kp + 64 * 72), qa = qsp[0], qb = qsp[4 * 64];
;                 __builtin_amdgcn_sched_group_barrier(0x100, 4, 0);
; #pragma unroll
;                 for (int ks = 0; ks < 4; ++ks) { bf16x8 ka2 = ka, kb2 = kb, qa2 = qa, qb2 = qb;
;                     if (ks < 3) { ka2 = *(const LAS bf16x8*)(kp + (ks + 1) * 16); kb2 = *(const LAS bf16x8*)(kp + 64 * 72 + (ks + 1) * 16); qa2 = qsp[(ks + 1) * 64]; qb2 = qsp[(4 + ks + 1) * 64];
;                         __builtin_amdgcn_sched_group_barrier(0x100, 4, 0); }
;                     s0 = __builtin_amdgcn_mfma_f32_32x32x16_bf16(ka, qa, s0, 0, 0, 0);
;                     s1 = __builtin_amdgcn_mfma_f32_32x32x16_bf16(kb, qb, s1, 0, 0, 0);
;                     __builtin_amdgcn_sched_group_barrier(0x008, 2, 0);
;                     ka = ka2; kb = kb2; qa = qa2; qb = qb2; }
;             }
.LBB0_227:
	v_lshl_add_u64 v[128:129], v[184:185], 0, s[16:17]
	s_mov_b32 s18, 0x1b020000
	v_add_co_u32_e32 v128, vcc, s18, v128
	v_lshl_add_u64 v[130:131], v[182:183], 0, s[16:17]
	s_nop 0
	v_addc_co_u32_e32 v129, vcc, 0, v129, vcc
	global_load_dwordx4 v[168:171], v[128:129], off
	global_load_dwordx4 v[172:175], v[128:129], off offset:128
	v_add_co_u32_e32 v128, vcc, 0xb020000, v130
	s_add_i32 s18, s58, 0xffffff50
	s_nop 0
	v_addc_co_u32_e32 v129, vcc, 0, v131, vcc
	global_load_dwordx4 v[164:167], v[128:129], off
	global_load_dwordx4 v[160:163], v[128:129], off offset:16
	s_cmp_gt_i32 s18, s35
	s_cbranch_scc1 .LBB0_226
	s_bitcmp1_b32 s59, 0
	s_cselect_b32 s18, 0x9000, 0
	s_add_i32 s38, s18, 0
	v_add3_u32 v199, s38, v208, v192
	ds_read_b128 v[138:141], v199
	ds_read_b128 v[200:203], v199 offset:9216
	ds_read_b128 v[204:207], v189
	ds_read_b128 v[218:221], v189 offset:4096
	v_xor_b32_e32 v144, 0x80000000, v190
	v_xor_b32_e32 v128, 0x80000000, v191
	v_mov_b32_e32 v145, v144
	v_mov_b64_e32 v[146:147], v[144:145]
	v_mov_b64_e32 v[148:149], v[144:145]
	v_mov_b64_e32 v[150:151], v[144:145]
	v_mov_b64_e32 v[152:153], v[144:145]
	v_mov_b64_e32 v[154:155], v[144:145]
	v_mov_b64_e32 v[156:157], v[144:145]
	v_mov_b64_e32 v[158:159], v[144:145]
	v_mov_b32_e32 v129, v128
	v_mov_b64_e32 v[130:131], v[128:129]
	v_mov_b64_e32 v[132:133], v[128:129]
	v_mov_b64_e32 v[134:135], v[128:129]
	v_mov_b64_e32 v[136:137], v[128:129]
	ds_read_b128 v[222:225], v199 offset:32
	ds_read_b128 v[226:229], v199 offset:9248
	ds_read_b128 v[230:233], v189 offset:1024
	ds_read_b128 v[234:237], v189 offset:5120
	s_waitcnt lgkmcnt(5)
	v_mfma_f32_32x32x16_bf16 v[144:159], v[138:141], v[204:207], v[144:159]
	v_mov_b64_e32 v[142:143], v[128:129]
	v_mov_b64_e32 v[138:139], v[128:129]
	v_mov_b64_e32 v[140:141], v[128:129]
	s_sub_i32 s18, s58, 32
	s_cmp_le_i32 s18, s31
	s_waitcnt lgkmcnt(4)
	v_mfma_f32_32x32x16_bf16 v[128:143], v[200:203], v[218:221], v[128:143]
	ds_read_b128 v[200:203], v199 offset:64
	ds_read_b128 v[204:207], v199 offset:9280
	ds_read_b128 v[218:221], v189 offset:2048
	ds_read_b128 v[238:241], v189 offset:6144
	s_waitcnt lgkmcnt(5)
	v_mfma_f32_32x32x16_bf16 v[144:159], v[222:225], v[230:233], v[144:159]
	s_waitcnt lgkmcnt(4)
	v_mfma_f32_32x32x16_bf16 v[128:143], v[226:229], v[234:237], v[128:143]
	ds_read_b128 v[222:225], v199 offset:96
	ds_read_b128 v[226:229], v199 offset:9312
	ds_read_b128 v[230:233], v189 offset:3072
	ds_read_b128 v[234:237], v189 offset:7168
	s_waitcnt lgkmcnt(5)
	v_mfma_f32_32x32x16_bf16 v[144:159], v[200:203], v[218:221], v[144:159]
	s_cbranch_scc0 .Lqk_diag0
	s_waitcnt lgkmcnt(1)
	v_mfma_f32_32x32x16_bf16 v[144:159], v[222:225], v[230:233], v[144:159]
	v_add3_u32 v219, s38, v193, v192
	ds_read_b128 v[212:215], v219 offset:32256
	ds_read_b128 v[220:223], v219 offset:18432
	v_mfma_f32_32x32x16_bf16 v[128:143], v[204:207], v[238:241], v[128:143]
	s_waitcnt lgkmcnt(2)
	v_mfma_f32_32x32x16_bf16 v[128:143], v[226:229], v[234:237], v[128:143]
	ds_read_b128 v[228:231], v219 offset:23040
	ds_read_b128 v[232:235], v219 offset:23072
	ds_read_b128 v[236:239], v219 offset:27648
	ds_read_b128 v[240:243], v219 offset:27680
	s_nop 1
; #define LAS __attribute__((address_space(3)))
; __device__ __forceinline__ void dattn_unit(LAS unsigned char* lds, int b, int h, int qb, const bf16* Q, const bf16* K, const bf16* V, bf16* YB, float lam, const float* subg, float oml, int tid) {
;     ...
;             for (int cb = 0; cb < 4; ++cb) { const LAS bf16* vp = Vt + (32 * cb + ql) * 72 + 32 * sub + 4 * hi;
;                 const v2u a0 = *(const LAS v2u*)(vp), a1 = *(const LAS v2u*)(vp + 8), a2 = *(const LAS v2u*)(vp + 16), a3 = *(const LAS v2u*)(vp + 24);
;                 const v4u f0 = {a0.x, a0.y, a1.x, a1.y}, f1 = {a2.x, a2.y, a3.x, a3.y};
;                 o[0][cb] = __builtin_amdgcn_mfma_f32_32x32x16_bf16(__builtin_bit_cast(bf16x8, f0), pA0, o[0][cb], 0, 0, 0);
;                 o[1][cb] = __builtin_amdgcn_mfma_f32_32x32x16_bf16(__builtin_bit_cast(bf16x8, f0), pA1, o[1][cb], 0, 0, 0);
;                 o[0][cb] = __builtin_amdgcn_mfma_f32_32x32x16_bf16(__builtin_bit_cast(bf16x8, f1), pB0, o[0][cb], 0, 0, 0);
;                 o[1][cb] = __builtin_amdgcn_mfma_f32_32x32x16_bf16(__builtin_bit_cast(bf16x8, f1), pB1, o[1][cb], 0, 0, 0); }
.Lsm0_0:
	v_exp_f32_e32 v201, v144
	v_exp_f32_e32 v202, v145
	v_exp_f32_e32 v203, v146
	v_exp_f32_e32 v204, v147
	v_exp_f32_e32 v205, v148
	v_add_f32_e32 v144, v202, v201
	v_exp_f32_e32 v206, v149
	v_add_f32_e32 v144, v203, v144
	v_exp_f32_e32 v207, v150
	v_add_f32_e32 v144, v204, v144
	v_exp_f32_e32 v218, v151
	v_add_f32_e32 v144, v205, v144
	v_exp_f32_e32 v147, v152
	v_add_f32_e32 v144, v206, v144
	v_exp_f32_e32 v148, v153
	v_add_f32_e32 v144, v207, v144
	v_exp_f32_e32 v149, v154
	v_add_f32_e32 v144, v218, v144
	v_exp_f32_e32 v150, v155
	v_add_f32_e32 v144, v147, v144
	v_exp_f32_e32 v151, v156
	v_add_f32_e32 v144, v148, v144
	v_exp_f32_e32 v152, v157
	v_add_f32_e32 v144, v149, v144
	v_exp_f32_e32 v153, v158
	v_add_f32_e32 v144, v150, v144
	v_exp_f32_e32 v154, v159
	v_add_f32_e32 v144, v151, v144
	v_add_f32_e32 v144, v152, v144
	v_add_f32_e32 v144, v153, v144
	v_add_f32_e32 v145, v154, v144
	v_cmp_lt_f32_e32 vcc, s82, v145
	s_cmp_lg_u64 vcc, 0
	s_cselect_b64 s[48:49], -1, 0
	s_cbranch_vccz .LBB0_232
	v_max_f32_e32 v146, v204, v204
	v_max_f32_e32 v155, v203, v203
	v_max_f32_e32 v146, v155, v146
	v_max_f32_e32 v155, v218, v218
	v_max_f32_e32 v156, v207, v207
	v_max_f32_e32 v155, v156, v155
	v_max_f32_e32 v156, v148, v148
	v_max_f32_e32 v157, v147, v147
	v_max_f32_e32 v156, v157, v156
	v_max_f32_e32 v157, v150, v150
	v_max_f32_e32 v158, v149, v149
	v_max_f32_e32 v157, v158, v157
	v_max_f32_e32 v158, v154, v154
	v_max_f32_e32 v159, v153, v153
	v_max_f32_e32 v158, v159, v158
	v_max3_f32 v158, v151, v152, v158
	v_max3_f32 v146, v201, v202, v146
	v_max3_f32 v155, v205, v206, v155
	v_max3_f32 v156, v156, v157, v158
	v_max3_f32 v146, v146, v155, v156
	v_mov_b32_e32 v155, v146
	s_nop 1
	v_permlane32_swap_b32_e32 v146, v155
	v_max_f32_e32 v155, v155, v155
	v_max_f32_e32 v146, v146, v146
	v_max_f32_e32 v146, v146, v155
.LBB0_232:
	v_cvt_pk_bf16_f32 v224, v201, v202
	v_cvt_pk_bf16_f32 v225, v203, v204
	v_cvt_pk_bf16_f32 v226, v205, v206
	v_cvt_pk_bf16_f32 v227, v207, v218
	v_cvt_pk_bf16_f32 v148, v147, v148
	v_cvt_pk_bf16_f32 v149, v149, v150
	v_cvt_pk_bf16_f32 v150, v151, v152
	v_cvt_pk_bf16_f32 v151, v153, v154
	ds_read_b128 v[204:207], v219 offset:18464
	ds_read_b128 v[200:203], v219 offset:32288
	v_add_f32_e32 v179, v179, v145
	v_exp_f32_e32 v155, v128
	v_exp_f32_e32 v129, v129
	v_exp_f32_e32 v130, v130
	v_exp_f32_e32 v131, v131
	s_waitcnt lgkmcnt(2)
	v_mfma_f32_32x32x16_bf16 v[80:95], v[228:231], v[224:227], v[80:95]
	v_exp_f32_e32 v132, v132
	v_add_f32_e32 v128, v129, v155
	v_exp_f32_e32 v156, v133
	v_mfma_f32_32x32x16_bf16 v[80:95], v[232:235], v[148:151], v[80:95]
	v_add_f32_e32 v128, v130, v128
	v_exp_f32_e32 v157, v134
	v_add_f32_e32 v128, v131, v128
	v_exp_f32_e32 v158, v135
	v_mfma_f32_32x32x16_bf16 v[48:63], v[236:239], v[224:227], v[48:63]
	v_add_f32_e32 v128, v132, v128
	v_exp_f32_e32 v133, v136
	v_add_f32_e32 v128, v156, v128
	v_exp_f32_e32 v134, v137
	v_mfma_f32_32x32x16_bf16 v[48:63], v[240:243], v[148:151], v[48:63]
	v_add_f32_e32 v128, v157, v128
	v_exp_f32_e32 v135, v138
	v_add_f32_e32 v128, v158, v128
	v_exp_f32_e32 v136, v139
	v_mfma_f32_32x32x16_bf16 v[16:31], v[212:215], v[224:227], v[16:31]
	v_add_f32_e32 v128, v133, v128
	v_exp_f32_e32 v137, v140
	v_add_f32_e32 v128, v134, v128
	v_exp_f32_e32 v138, v141
	v_mfma_f32_32x32x16_bf16 v[112:127], v[220:223], v[224:227], v[112:127]
	v_add_f32_e32 v128, v135, v128
	v_exp_f32_e32 v139, v142
	v_add_f32_e32 v128, v136, v128
	v_exp_f32_e32 v140, v143
	s_waitcnt lgkmcnt(1)
	v_mfma_f32_32x32x16_bf16 v[112:127], v[204:207], v[148:151], v[112:127]
	v_add_f32_e32 v128, v137, v128
	v_add_f32_e32 v128, v138, v128
	v_add_f32_e32 v128, v139, v128
	v_add_f32_e32 v128, v140, v128
	s_waitcnt lgkmcnt(0)
	v_mfma_f32_32x32x16_bf16 v[16:31], v[200:203], v[148:151], v[16:31]
	v_cmp_lt_f32_e32 vcc, s82, v128
	s_cmp_lg_u64 vcc, 0
	s_cselect_b64 s[46:47], -1, 0
	s_cbranch_vccz .LBB0_234
	v_max_f32_e32 v141, v131, v131
	v_max_f32_e32 v142, v130, v130
	v_max_f32_e32 v141, v142, v141
	v_max_f32_e32 v142, v158, v158
	v_max_f32_e32 v143, v157, v157
	v_max_f32_e32 v142, v143, v142
	v_max_f32_e32 v143, v134, v134
	v_max_f32_e32 v144, v133, v133
	v_max_f32_e32 v143, v144, v143
	v_max_f32_e32 v144, v136, v136
	v_max_f32_e32 v159, v135, v135
	v_max_f32_e32 v144, v159, v144
	v_max_f32_e32 v159, v140, v140
	v_max_f32_e32 v147, v139, v139
	v_max_f32_e32 v159, v147, v159
	v_max3_f32 v159, v137, v138, v159
	v_max3_f32 v141, v155, v129, v141
	v_max3_f32 v142, v132, v156, v142
	v_max3_f32 v143, v143, v144, v159
	v_max3_f32 v141, v141, v142, v143
	v_mov_b32_e32 v142, v141
	s_nop 1
	v_permlane32_swap_b32_e32 v141, v142
	v_max_f32_e32 v142, v142, v142
	v_max_f32_e32 v141, v141, v141
	v_max_f32_e32 v144, v141, v142

; #define LAS __attribute__((address_space(3)))
; __device__ __forceinline__ void dattn_unit(LAS unsigned char* lds, int b, int h, int qb, const bf16* Q, const bf16* K, const bf16* V, bf16* YB, float lam, const float* subg, float oml, int tid) {
;     ...
; #pragma unroll
;         for (int sub = 0; sub < 2; ++sub) {
;             if (kvbase + 32 * sub > qmax) continue;
;             const bool need_bm = kvbase + 32 * sub + 31 + 113 > qmin;
;             LAS bf16x8* qsp = qs; asm volatile("" : "+v"(qsp));
;             f32x16 s0, s1;
; #pragma unroll
;             for (int r = 0; r < 16; ++r) { s0[r] = -mref[0]; s1[r] = -mref[1]; }
;             {
;                 const LAS bf16* kp = Ks + (32 * sub + ql) * 72 + hi * 8;
;                 bf16x8 ka = *(const LAS bf16x8*)kp, kb = *(const LAS bf16x8*)(kp + 64 * 72), qa = qsp[0], qb = qsp[4 * 64];
;                 __builtin_amdgcn_sched_group_barrier(0x100, 4, 0);
; #pragma unroll
;                 for (int ks = 0; ks < 4; ++ks) { bf16x8 ka2 = ka, kb2 = kb, qa2 = qa, qb2 = qb;
;                     if (ks < 3) { ka2 = *(const LAS bf16x8*)(kp + (ks + 1) * 16); kb2 = *(const LAS bf16x8*)(kp + 64 * 72 + (ks + 1) * 16); qa2 = qsp[(ks + 1) * 64]; qb2 = qsp[(4 + ks + 1) * 64];
;                         __builtin_amdgcn_sched_group_barrier(0x100, 4, 0); }
;                     s0 = __builtin_amdgcn_mfma_f32_32x32x16_bf16(ka, qa, s0, 0, 0, 0);
;                     s1 = __builtin_amdgcn_mfma_f32_32x32x16_bf16(kb, qb, s1, 0, 0, 0);
;                     __builtin_amdgcn_sched_group_barrier(0x008, 2, 0);
;                     ka = ka2; kb = kb2; qa = qa2; qb = qb2; }
;             }
.LBB0_238:
	s_add_i32 s18, s58, 0xffffff70
	s_cmp_gt_i32 s18, s35
	s_cbranch_scc1 .LBB0_226
	ds_read_b128 v[138:141], v199 offset:4608
	ds_read_b128 v[204:207], v199 offset:13824
	ds_read_b128 v[218:221], v189
	ds_read_b128 v[222:225], v189 offset:4096
	v_xor_b32_e32 v144, 0x80000000, v190
	v_xor_b32_e32 v128, 0x80000000, v191
	v_mov_b32_e32 v145, v144
	v_mov_b64_e32 v[146:147], v[144:145]
	v_mov_b64_e32 v[148:149], v[144:145]
	v_mov_b64_e32 v[150:151], v[144:145]
	v_mov_b64_e32 v[152:153], v[144:145]
	v_mov_b64_e32 v[154:155], v[144:145]
	v_mov_b64_e32 v[156:157], v[144:145]
	v_mov_b64_e32 v[158:159], v[144:145]
	v_mov_b32_e32 v129, v128
	v_mov_b64_e32 v[130:131], v[128:129]
	v_mov_b64_e32 v[132:133], v[128:129]
	v_mov_b64_e32 v[134:135], v[128:129]
	v_mov_b64_e32 v[136:137], v[128:129]
	ds_read_b128 v[226:229], v199 offset:4640
	ds_read_b128 v[230:233], v199 offset:13856
	ds_read_b128 v[234:237], v189 offset:1024
	ds_read_b128 v[238:241], v189 offset:5120
	s_waitcnt lgkmcnt(5)
	v_mfma_f32_32x32x16_bf16 v[144:159], v[138:141], v[218:221], v[144:159]
	v_mov_b64_e32 v[142:143], v[128:129]
	v_mov_b64_e32 v[138:139], v[128:129]
	v_mov_b64_e32 v[140:141], v[128:129]
	s_cmp_le_i32 s58, s31
	s_waitcnt lgkmcnt(4)
	v_mfma_f32_32x32x16_bf16 v[128:143], v[204:207], v[222:225], v[128:143]
	ds_read_b128 v[204:207], v199 offset:4672
	ds_read_b128 v[218:221], v199 offset:13888
	ds_read_b128 v[222:225], v189 offset:2048
	ds_read_b128 v[212:215], v189 offset:6144
	s_waitcnt lgkmcnt(5)
	v_mfma_f32_32x32x16_bf16 v[144:159], v[226:229], v[234:237], v[144:159]
	s_waitcnt lgkmcnt(4)
	v_mfma_f32_32x32x16_bf16 v[128:143], v[230:233], v[238:241], v[128:143]
	ds_read_b128 v[226:229], v199 offset:4704
	ds_read_b128 v[230:233], v199 offset:13920
	ds_read_b128 v[234:237], v189 offset:3072
	ds_read_b128 v[238:241], v189 offset:7168
	s_waitcnt lgkmcnt(5)
	v_mfma_f32_32x32x16_bf16 v[144:159], v[204:207], v[222:225], v[144:159]
	s_cbranch_scc0 .Lqk_diag1
	s_waitcnt lgkmcnt(1)
	v_mfma_f32_32x32x16_bf16 v[144:159], v[226:229], v[234:237], v[144:159]
	v_add3_u32 v243, s38, v193, v192
	ds_read_b128 v[222:225], v243 offset:23104
	ds_read_b128 v[226:229], v243 offset:23136
	v_mfma_f32_32x32x16_bf16 v[128:143], v[218:221], v[212:215], v[128:143]
	s_waitcnt lgkmcnt(2)
	v_mfma_f32_32x32x16_bf16 v[128:143], v[230:233], v[238:241], v[128:143]
	ds_read_b128 v[230:233], v243 offset:27712
	ds_read_b128 v[234:237], v243 offset:27744
	ds_read_b128 v[238:241], v243 offset:32320
	ds_read_b128 v[212:215], v243 offset:18496
	ds_read_b128 v[200:203], v243 offset:18528
	s_nop 1
.Lsm0_1:
	v_exp_f32_e32 v199, v144
	v_exp_f32_e32 v204, v145
	v_exp_f32_e32 v205, v146
	v_exp_f32_e32 v206, v147
	v_exp_f32_e32 v207, v148
	v_add_f32_e32 v144, v204, v199
	v_exp_f32_e32 v218, v149
	v_add_f32_e32 v144, v205, v144
	v_exp_f32_e32 v219, v150
	v_add_f32_e32 v144, v206, v144
	v_exp_f32_e32 v220, v151
	v_add_f32_e32 v144, v207, v144
	v_exp_f32_e32 v147, v152
	v_add_f32_e32 v144, v218, v144
	v_exp_f32_e32 v148, v153
	v_add_f32_e32 v144, v219, v144
	v_exp_f32_e32 v149, v154
	v_add_f32_e32 v144, v220, v144
	v_exp_f32_e32 v150, v155
	v_add_f32_e32 v144, v147, v144
	v_exp_f32_e32 v151, v156
	v_add_f32_e32 v144, v148, v144
	v_exp_f32_e32 v152, v157
	v_add_f32_e32 v144, v149, v144
	v_exp_f32_e32 v153, v158
	v_add_f32_e32 v144, v150, v144
	v_exp_f32_e32 v154, v159
	v_add_f32_e32 v144, v151, v144
	v_add_f32_e32 v144, v152, v144
	v_add_f32_e32 v144, v153, v144
	v_add_f32_e32 v145, v154, v144
	v_cmp_lt_f32_e32 vcc, s82, v145
	s_cmp_lg_u64 vcc, 0
	s_cselect_b64 s[48:49], -1, 0
	s_cbranch_vccz .LBB0_243
	v_max_f32_e32 v146, v206, v206
	v_max_f32_e32 v155, v205, v205
	v_max_f32_e32 v146, v155, v146
	v_max_f32_e32 v155, v220, v220
	v_max_f32_e32 v156, v219, v219
	v_max_f32_e32 v155, v156, v155
	v_max_f32_e32 v156, v148, v148
	v_max_f32_e32 v157, v147, v147
	v_max_f32_e32 v156, v157, v156
	v_max_f32_e32 v157, v150, v150
	v_max_f32_e32 v158, v149, v149
	v_max_f32_e32 v157, v158, v157
	v_max_f32_e32 v158, v154, v154
	v_max_f32_e32 v159, v153, v153
	v_max_f32_e32 v158, v159, v158
	v_max3_f32 v158, v151, v152, v158
	v_max3_f32 v146, v199, v204, v146
	v_max3_f32 v155, v207, v218, v155
	v_max3_f32 v156, v156, v157, v158
	v_max3_f32 v146, v146, v155, v156
	v_mov_b32_e32 v155, v146
	s_nop 1
	v_permlane32_swap_b32_e32 v146, v155
	v_max_f32_e32 v155, v155, v155
	v_max_f32_e32 v146, v146, v146
	v_max_f32_e32 v146, v146, v155
; __device__ __forceinline__ void dattn_unit(LAS unsigned char* lds, int b, int h, int qb, const bf16* Q, const bf16* K, const bf16* V, bf16* YB, float lam, const float* subg, float oml, int tid) {
;     ...
; #pragma unroll
;         for (int sub = 0; sub < 2; ++sub) {
;             if (kvbase + 32 * sub > qmax) continue;
;             const bool need_bm = kvbase + 32 * sub + 31 + 113 > qmin;
;             LAS bf16x8* qsp = qs; asm volatile("" : "+v"(qsp));
;             f32x16 s0, s1;
; #pragma unroll
;             for (int r = 0; r < 16; ++r) { s0[r] = -mref[0]; s1[r] = -mref[1]; }
;             {
;                 const LAS bf16* kp = Ks + (32 * sub + ql) * 72 + hi * 8;
;                 bf16x8 ka = *(const LAS bf16x8*)kp, kb = *(const LAS bf16x8*)(kp + 64 * 72), qa = qsp[0], qb = qsp[4 * 64];
;                 __builtin_amdgcn_sched_group_barrier(0x100, 4, 0);
; #pragma unroll
;                 for (int ks = 0; ks < 4; ++ks) { bf16x8 ka2 = ka, kb2 = kb, qa2 = qa, qb2 = qb;
;                     if (ks < 3) { ka2 = *(const LAS bf16x8*)(kp + (ks + 1) * 16); kb2 = *(const LAS bf16x8*)(kp + 64 * 72 + (ks + 1) * 16); qa2 = qsp[(ks + 1) * 64]; qb2 = qsp[(4 + ks + 1) * 64];
;                         __builtin_amdgcn_sched_group_barrier(0x100, 4, 0); }
;                     s0 = __builtin_amdgcn_mfma_f32_32x32x16_bf16(ka, qa, s0, 0, 0, 0);
;                     s1 = __builtin_amdgcn_mfma_f32_32x32x16_bf16(kb, qb, s1, 0, 0, 0);
;                     __builtin_amdgcn_sched_group_barrier(0x008, 2, 0);
;                     ka = ka2; kb = kb2; qa = qa2; qb = qb2; }
;             }
;             if (need_bm) { const LAS float* gb = tab + (159 - (q - (kvbase + 32 * sub + 4 * hi)));
; #pragma unroll
;                 for (int r = 0; r < 16; ++r) { const float bv = gb[(r & 3) + 8 * (r >> 2)]; s0[r] += bv; s1[r] += bv; } }
;             bf16x8 pA0, pB0, pA1, pB1; bool trig[2]; float pmx[2] = {1.f, 1.f};
;             AT_SOFTMAX(s0, 0, pA0, pB0);
;             AT_SOFTMAX(s1, 1, pA1, pB1);
; #pragma unroll
;             for (int cb = 0; cb < 4; ++cb) { const LAS bf16* vp = Vt + (32 * cb + ql) * 72 + 32 * sub + 4 * hi;
;                 const v2u a0 = *(const LAS v2u*)(vp), a1 = *(const LAS v2u*)(vp + 8), a2 = *(const LAS v2u*)(vp + 16), a3 = *(const LAS v2u*)(vp + 24);
;                 const v4u f0 = {a0.x, a0.y, a1.x, a1.y}, f1 = {a2.x, a2.y, a3.x, a3.y};
.LBB0_243:
	v_cvt_pk_bf16_f32 v205, v205, v206
	v_cvt_pk_bf16_f32 v206, v207, v218
	v_cvt_pk_bf16_f32 v207, v219, v220
	v_cvt_pk_bf16_f32 v204, v199, v204
	v_cvt_pk_bf16_f32 v148, v147, v148
	v_cvt_pk_bf16_f32 v149, v149, v150
	v_cvt_pk_bf16_f32 v150, v151, v152
	v_cvt_pk_bf16_f32 v151, v153, v154
	ds_read_b128 v[218:221], v243 offset:32352
	v_add_f32_e32 v179, v179, v145
	v_exp_f32_e32 v155, v128
	v_exp_f32_e32 v129, v129
	v_exp_f32_e32 v130, v130
	v_exp_f32_e32 v131, v131
	s_waitcnt lgkmcnt(1)
	v_mfma_f32_32x32x16_bf16 v[80:95], v[222:225], v[204:207], v[80:95]
	v_exp_f32_e32 v132, v132
	v_add_f32_e32 v128, v129, v155
	v_exp_f32_e32 v156, v133
	v_mfma_f32_32x32x16_bf16 v[80:95], v[226:229], v[148:151], v[80:95]
	v_add_f32_e32 v128, v130, v128
	v_exp_f32_e32 v157, v134
	v_add_f32_e32 v128, v131, v128
	v_exp_f32_e32 v158, v135
	v_mfma_f32_32x32x16_bf16 v[48:63], v[230:233], v[204:207], v[48:63]
	v_add_f32_e32 v128, v132, v128
	v_exp_f32_e32 v133, v136
	v_add_f32_e32 v128, v156, v128
	v_exp_f32_e32 v134, v137
	v_mfma_f32_32x32x16_bf16 v[48:63], v[234:237], v[148:151], v[48:63]
	v_add_f32_e32 v128, v157, v128
	v_exp_f32_e32 v135, v138
	v_add_f32_e32 v128, v158, v128
	v_exp_f32_e32 v136, v139
	v_mfma_f32_32x32x16_bf16 v[16:31], v[238:241], v[204:207], v[16:31]
	v_add_f32_e32 v128, v133, v128
	v_exp_f32_e32 v137, v140
	v_add_f32_e32 v128, v134, v128
	v_exp_f32_e32 v138, v141
	v_mfma_f32_32x32x16_bf16 v[112:127], v[212:215], v[204:207], v[112:127]
	v_add_f32_e32 v128, v135, v128
	v_exp_f32_e32 v139, v142
	v_add_f32_e32 v128, v136, v128
	v_exp_f32_e32 v140, v143
	v_mfma_f32_32x32x16_bf16 v[112:127], v[200:203], v[148:151], v[112:127]
	v_add_f32_e32 v128, v137, v128
	v_add_f32_e32 v128, v138, v128
	v_add_f32_e32 v128, v139, v128
	v_add_f32_e32 v128, v140, v128
	s_waitcnt lgkmcnt(0)
	v_mfma_f32_32x32x16_bf16 v[16:31], v[218:221], v[148:151], v[16:31]
	v_cmp_lt_f32_e32 vcc, s82, v128
	s_cmp_lg_u64 vcc, 0
	s_cselect_b64 s[46:47], -1, 0
	s_cbranch_vccz .LBB0_245
	v_max_f32_e32 v141, v131, v131
	v_max_f32_e32 v142, v130, v130
	v_max_f32_e32 v141, v142, v141
	v_max_f32_e32 v142, v158, v158
	v_max_f32_e32 v143, v157, v157
	v_max_f32_e32 v142, v143, v142
	v_max_f32_e32 v143, v134, v134
	v_max_f32_e32 v144, v133, v133
	v_max_f32_e32 v143, v144, v143
	v_max_f32_e32 v144, v136, v136
	v_max_f32_e32 v159, v135, v135
	v_max_f32_e32 v144, v159, v144
	v_max_f32_e32 v159, v140, v140
	v_max_f32_e32 v147, v139, v139
	v_max_f32_e32 v159, v147, v159
	v_max3_f32 v159, v137, v138, v159
	v_max3_f32 v141, v155, v129, v141
	v_max3_f32 v142, v132, v156, v142
	v_max3_f32 v143, v143, v144, v159
	v_max3_f32 v141, v141, v142, v143
	v_mov_b32_e32 v142, v141
	s_nop 1
	v_permlane32_swap_b32_e32 v141, v142
	v_max_f32_e32 v142, v142, v142
	v_max_f32_e32 v141, v141, v141
	v_max_f32_e32 v144, v141, v142
